# v4 + RMSNorm/QK-norm row scales in S3/S6 epilogues via v_rsq_f32 instead of the expanded sqrt+divide
# speedup vs baseline: 1.0212x; 1.0016x over previous
.LBB0_600:
	s_lshl_b32 s36, s10, 8
	v_cndmask_b32_e64 v128, 0, 1, s[24:25]
	v_add_u32_e32 v186, s36, v172
	v_cmp_ne_u32_e64 s[10:11], 1, v128
	s_andn2_b64 vcc, exec, s[24:25]
	v_ashrrev_i32_e32 v187, 31, v186
	s_cbranch_vccnz .LBB0_602
	v_lshl_add_u64 v[128:129], v[186:187], 2, s[18:19]
	global_load_dword v128, v[128:129], off
	s_waitcnt vmcnt(0) lgkmcnt(0)
	v_fmamk_f32 v128, v128, 0x3a000000, v208
	s_nop 1
	s_nop 0
	s_nop 1
	s_nop 1
	s_nop 1
	v_rsq_f32_e32 v158, v128
	s_nop 0
	s_branch .LBB0_603

.LBB0_607:
	s_or_b64 exec, exec, s[4:5]
	s_and_b64 vcc, exec, s[10:11]
	s_cbranch_vccnz .LBB0_609
	s_ashr_i32 s37, s36, 31
	v_lshl_add_u64 v[128:129], s[36:37], 0, v[172:173]
	v_lshl_add_u64 v[128:129], v[128:129], 2, s[18:19]
	global_load_dword v128, v[128:129], off offset:64
	s_waitcnt vmcnt(0) lgkmcnt(0)
	v_fmamk_f32 v128, v128, 0x3a000000, v208
	s_nop 1
	s_nop 0
	s_nop 1
	s_nop 1
	s_nop 1
	v_rsq_f32_e32 v156, v128
	s_nop 0
	s_branch .LBB0_610

.LBB0_614:
	s_or_b64 exec, exec, s[4:5]
	s_and_b64 vcc, exec, s[10:11]
	s_cbranch_vccnz .LBB0_616
	s_ashr_i32 s37, s36, 31
	v_lshl_add_u64 v[128:129], s[36:37], 0, v[172:173]
	v_lshl_add_u64 v[128:129], v[128:129], 2, s[18:19]
	global_load_dword v128, v[128:129], off offset:128
	s_waitcnt vmcnt(0) lgkmcnt(0)
	v_fmamk_f32 v128, v128, 0x3a000000, v208
	s_nop 1
	s_nop 0
	s_nop 1
	s_nop 1
	s_nop 1
	v_rsq_f32_e32 v154, v128
	s_nop 0
	s_branch .LBB0_617

.LBB0_621:
	s_or_b64 exec, exec, s[4:5]
	s_and_b64 vcc, exec, s[10:11]
	s_cbranch_vccnz .LBB0_623
	s_ashr_i32 s37, s36, 31
	v_lshl_add_u64 v[128:129], s[36:37], 0, v[172:173]
	v_lshl_add_u64 v[128:129], v[128:129], 2, s[18:19]
	global_load_dword v128, v[128:129], off offset:192
	s_waitcnt vmcnt(0) lgkmcnt(0)
	v_fmamk_f32 v128, v128, 0x3a000000, v208
	s_nop 1
	s_nop 0
	s_nop 1
	s_nop 1
	s_nop 1
	v_rsq_f32_e32 v152, v128
	s_nop 0
	s_branch .LBB0_624

.LBB0_628:
	s_or_b64 exec, exec, s[4:5]
	s_and_b64 vcc, exec, s[10:11]
	s_cbranch_vccnz .LBB0_630
	s_ashr_i32 s37, s36, 31
	v_lshl_add_u64 v[128:129], s[36:37], 0, v[172:173]
	v_lshl_add_u64 v[128:129], v[128:129], 2, s[18:19]
	global_load_dword v128, v[128:129], off offset:512
	s_waitcnt vmcnt(0) lgkmcnt(0)
	v_fmamk_f32 v128, v128, 0x3a000000, v208
	s_nop 1
	s_nop 0
	s_nop 1
	s_nop 1
	s_nop 1
	v_rsq_f32_e32 v142, v128
	s_nop 0
	s_branch .LBB0_631

.LBB0_635:
	s_or_b64 exec, exec, s[4:5]
	s_and_b64 vcc, exec, s[10:11]
	s_cbranch_vccnz .LBB0_637
	s_ashr_i32 s37, s36, 31
	v_lshl_add_u64 v[128:129], s[36:37], 0, v[172:173]
	v_lshl_add_u64 v[128:129], v[128:129], 2, s[18:19]
	global_load_dword v128, v[128:129], off offset:576
	s_waitcnt vmcnt(0) lgkmcnt(0)
	v_fmamk_f32 v128, v128, 0x3a000000, v208
	s_nop 1
	s_nop 0
	s_nop 1
	s_nop 1
	s_nop 1
	v_rsq_f32_e32 v136, v128
	s_nop 0
	s_branch .LBB0_638

.LBB0_642:
	s_or_b64 exec, exec, s[4:5]
	s_and_b64 vcc, exec, s[10:11]
	s_cbranch_vccnz .LBB0_644
	s_ashr_i32 s37, s36, 31
	v_lshl_add_u64 v[128:129], s[36:37], 0, v[172:173]
	v_lshl_add_u64 v[128:129], v[128:129], 2, s[18:19]
	global_load_dword v128, v[128:129], off offset:640
	s_waitcnt vmcnt(0) lgkmcnt(0)
	v_fmamk_f32 v128, v128, 0x3a000000, v208
	s_nop 1
	s_nop 0
	s_nop 1
	s_nop 1
	s_nop 1
	v_rsq_f32_e32 v130, v128
	s_nop 0
	s_branch .LBB0_645

.LBB0_649:
	s_or_b64 exec, exec, s[4:5]
	s_and_b64 vcc, exec, s[10:11]
	s_cbranch_vccnz .LBB0_651
	s_ashr_i32 s37, s36, 31
	v_lshl_add_u64 v[128:129], s[36:37], 0, v[172:173]
	v_lshl_add_u64 v[128:129], v[128:129], 2, s[18:19]
	global_load_dword v128, v[128:129], off offset:704
	s_waitcnt vmcnt(0) lgkmcnt(0)
	v_fmamk_f32 v128, v128, 0x3a000000, v208
	s_nop 1
	s_nop 0
	s_nop 1
	s_nop 1
	s_nop 1
	v_rsq_f32_e32 v128, v128
	s_nop 0
	s_branch .LBB0_652

.LBB0_664:
	v_mov_b64_e32 v[162:163], v[160:161]
	v_mov_b64_e32 v[160:161], v[158:159]
	s_and_b64 vcc, exec, s[12:13]
	v_mov_b32_e32 v161, v158
	s_cbranch_vccnz .LBB0_666
	v_add_u32_e32 v129, 0, v189
	v_add_u32_e32 v129, 0x20000, v129
	ds_read_b128 v[160:163], v129
	s_waitcnt lgkmcnt(0)
	v_mov_b32_e32 v212, v161
	v_mov_b32_e32 v213, v162
	v_mov_b32_e32 v161, v163
	v_pk_add_f32 v[160:161], v[212:213], v[160:161]
	s_nop 0
	v_add_f32_e32 v129, v160, v161
	v_fmamk_f32 v129, v129, 0x3c000000, v208
	s_nop 1
	s_nop 0
	s_nop 1
	s_nop 1
	s_nop 1
	s_nop 0
	v_rsq_f32_e32 v129, v129
	s_nop 0
	v_mul_f32_e32 v160, v158, v129
	v_mov_b32_e32 v161, v160
.LBB0_666:
	s_ashr_i32 s39, s38, 31
	s_lshl_b64 s[16:17], s[38:39], 22
	v_lshlrev_b64 v[162:163], 8, v[186:187]
	s_add_u32 s38, s45, s16
	s_waitcnt vmcnt(0) lgkmcnt(0)
	v_pk_mul_f32 v[186:187], v[144:145], v[160:161]
	v_mov_b32_e32 v204, v161
	s_addc_u32 s39, s49, s17
	v_pk_mul_f32 v[160:161], v[148:149], v[160:161]
	v_pk_mul_f32 v[214:215], v[150:151], v[204:205] op_sel_hi:[1,0]
	v_pk_mul_f32 v[124:125], v[124:125], v[186:187]
	v_pk_mul_f32 v[186:187], v[122:123], v[214:215]
	v_pk_mul_f32 v[122:123], v[120:121], v[160:161]
	v_cvt_pk_bf16_f32 v120, v124, v125
	v_lshl_add_u64 v[124:125], s[38:39], 0, v[162:163]
	v_pk_mul_f32 v[212:213], v[146:147], v[204:205] op_sel_hi:[1,0]
	v_lshl_add_u64 v[124:125], v[174:175], 1, v[124:125]
	s_and_b64 vcc, exec, s[10:11]
	v_pk_mul_f32 v[126:127], v[126:127], v[212:213]
	s_nop 0
	v_cvt_pk_bf16_f32 v121, v126, v127
	v_cvt_pk_bf16_f32 v122, v122, v123
	v_cvt_pk_bf16_f32 v123, v186, v187
	global_store_dwordx4 v[124:125], v[120:123], off
	s_cbranch_vccnz .LBB0_668
	s_add_i32 s5, 0, 0x20000
	v_add_u32_e32 v120, s5, v189
	ds_read_b128 v[120:123], v120 offset:16
	s_waitcnt lgkmcnt(0)
	v_mov_b32_e32 v124, v121
	v_mov_b32_e32 v125, v122
	v_mov_b32_e32 v121, v123
	v_pk_add_f32 v[120:121], v[124:125], v[120:121]
	s_nop 0
	v_add_f32_e32 v120, v120, v121
	v_fmamk_f32 v120, v120, 0x3c000000, v208
	s_nop 1
	s_nop 0
	s_nop 1
	s_nop 1
	s_nop 1
	s_nop 0
	v_rsq_f32_e32 v120, v120
	s_nop 0
	v_mul_f32_e32 v158, v158, v120
.LBB0_668:
	s_ashr_i32 s5, s4, 31
	v_mov_b32_e32 v159, v158
	s_lshl_b64 s[4:5], s[4:5], 22
	s_add_u32 s46, s45, s4
	v_pk_mul_f32 v[120:121], v[132:133], v[158:159]
	v_mov_b32_e32 v122, v158
	s_addc_u32 s47, s49, s5
	v_pk_mul_f32 v[124:125], v[134:135], v[122:123] op_sel_hi:[1,0]
	v_pk_mul_f32 v[126:127], v[138:139], v[158:159]
	v_pk_mul_f32 v[122:123], v[140:141], v[122:123] op_sel_hi:[1,0]
	v_pk_mul_f32 v[116:117], v[116:117], v[120:121]
	v_pk_mul_f32 v[120:121], v[114:115], v[122:123]
	v_pk_mul_f32 v[114:115], v[112:113], v[126:127]
	v_cvt_pk_bf16_f32 v112, v116, v117
	v_lshl_add_u64 v[116:117], s[46:47], 0, v[162:163]
	v_pk_mul_f32 v[118:119], v[118:119], v[124:125]
	v_lshl_add_u64 v[116:117], v[174:175], 1, v[116:117]
	v_cvt_pk_bf16_f32 v113, v118, v119
	v_cvt_pk_bf16_f32 v114, v114, v115
	v_cvt_pk_bf16_f32 v115, v120, v121
	global_store_dwordx4 v[116:117], v[112:115], off
	s_and_b64 vcc, exec, s[12:13]
	v_mov_b32_e32 v116, v156
	v_mov_b64_e32 v[112:113], v[156:157]
	v_mov_b64_e32 v[114:115], v[158:159]
	s_cbranch_vccnz .LBB0_670
	v_add_u32_e32 v112, 0, v191
	v_add_u32_e32 v112, 0x20000, v112
	ds_read_b128 v[112:115], v112
	s_waitcnt lgkmcnt(0)
	v_mov_b32_e32 v116, v113
	v_mov_b32_e32 v117, v114
	v_mov_b32_e32 v113, v115
	v_pk_add_f32 v[112:113], v[116:117], v[112:113]
	s_nop 0
	v_add_f32_e32 v112, v112, v113
	v_fmamk_f32 v112, v112, 0x3c000000, v208
	s_nop 1
	s_nop 0
	s_nop 1
	s_nop 1
	s_nop 1
	s_nop 0
	v_rsq_f32_e32 v112, v112
	s_nop 0
	v_mul_f32_e32 v112, v156, v112
	v_mov_b32_e32 v116, v112
.LBB0_670:
	v_add_u32_e32 v114, s36, v190
	v_mov_b32_e32 v113, v116
	v_ashrrev_i32_e32 v115, 31, v114
	v_pk_mul_f32 v[120:121], v[144:145], v[112:113]
	v_lshlrev_b64 v[114:115], 8, v[114:115]
	v_pk_mul_f32 v[118:119], v[146:147], v[116:117] op_sel_hi:[1,0]
	v_pk_mul_f32 v[116:117], v[150:151], v[116:117] op_sel_hi:[1,0]
	v_pk_mul_f32 v[112:113], v[148:149], v[112:113]
	v_pk_mul_f32 v[108:109], v[108:109], v[120:121]
	v_pk_mul_f32 v[116:117], v[106:107], v[116:117]
	v_pk_mul_f32 v[106:107], v[104:105], v[112:113]
	v_cvt_pk_bf16_f32 v104, v108, v109
	v_lshl_add_u64 v[108:109], s[38:39], 0, v[114:115]
	v_lshl_add_u64 v[108:109], v[174:175], 1, v[108:109]
	s_and_b64 vcc, exec, s[10:11]
	v_pk_mul_f32 v[110:111], v[110:111], v[118:119]
	s_nop 0
	v_cvt_pk_bf16_f32 v105, v110, v111
	v_cvt_pk_bf16_f32 v106, v106, v107
	v_cvt_pk_bf16_f32 v107, v116, v117
	global_store_dwordx4 v[108:109], v[104:107], off
	s_cbranch_vccnz .LBB0_672
	s_add_i32 s4, 0, 0x20000
	v_add_u32_e32 v104, s4, v191
	ds_read_b128 v[104:107], v104 offset:16
	s_waitcnt lgkmcnt(0)
	v_mov_b32_e32 v108, v105
	v_mov_b32_e32 v109, v106
	v_mov_b32_e32 v105, v107
	v_pk_add_f32 v[104:105], v[108:109], v[104:105]
	s_nop 0
	v_add_f32_e32 v104, v104, v105
	v_fmamk_f32 v104, v104, 0x3c000000, v208
	s_nop 1
	s_nop 0
	s_nop 1
	s_nop 1
	s_nop 1
	s_nop 0
	v_rsq_f32_e32 v104, v104
	s_nop 0
	v_mul_f32_e32 v156, v156, v104
.LBB0_672:
	s_nop 0
	v_pk_mul_f32 v[104:105], v[134:135], v[156:157] op_sel_hi:[1,0]
	v_mov_b32_e32 v157, v156
	v_pk_mul_f32 v[106:107], v[132:133], v[156:157]
	v_pk_mul_f32 v[108:109], v[140:141], v[156:157] op_sel_hi:[1,0]
	v_pk_mul_f32 v[110:111], v[138:139], v[156:157]
	v_pk_mul_f32 v[100:101], v[100:101], v[106:107]
	v_pk_mul_f32 v[102:103], v[102:103], v[104:105]
	v_pk_mul_f32 v[104:105], v[98:99], v[108:109]
	v_pk_mul_f32 v[98:99], v[96:97], v[110:111]
	v_cvt_pk_bf16_f32 v96, v100, v101
	v_lshl_add_u64 v[100:101], s[46:47], 0, v[114:115]
	v_cvt_pk_bf16_f32 v97, v102, v103
	v_cvt_pk_bf16_f32 v98, v98, v99
	v_cvt_pk_bf16_f32 v99, v104, v105
	v_lshl_add_u64 v[100:101], v[174:175], 1, v[100:101]
	global_store_dwordx4 v[100:101], v[96:99], off
	s_and_b64 vcc, exec, s[12:13]
	v_mov_b32_e32 v100, v154
	v_mov_b64_e32 v[96:97], v[154:155]
	v_mov_b64_e32 v[98:99], v[156:157]
	s_cbranch_vccnz .LBB0_674
	v_add_u32_e32 v96, 0, v193
	v_add_u32_e32 v96, 0x20000, v96
	ds_read_b128 v[96:99], v96
	s_waitcnt lgkmcnt(0)
	v_mov_b32_e32 v100, v97
	v_mov_b32_e32 v101, v98
	v_mov_b32_e32 v97, v99
	v_pk_add_f32 v[96:97], v[100:101], v[96:97]
	s_nop 0
	v_add_f32_e32 v96, v96, v97
	v_fmamk_f32 v96, v96, 0x3c000000, v208
	s_nop 1
	s_nop 0
	s_nop 1
	s_nop 1
	s_nop 1
	s_nop 0
	v_rsq_f32_e32 v96, v96
	s_nop 0
	v_mul_f32_e32 v96, v154, v96
	v_mov_b32_e32 v100, v96
.LBB0_674:
	v_add_u32_e32 v98, s36, v192
	v_mov_b32_e32 v97, v100
	v_ashrrev_i32_e32 v99, 31, v98
	v_pk_mul_f32 v[104:105], v[144:145], v[96:97]
	v_lshlrev_b64 v[98:99], 8, v[98:99]
	v_pk_mul_f32 v[102:103], v[146:147], v[100:101] op_sel_hi:[1,0]
	v_pk_mul_f32 v[100:101], v[150:151], v[100:101] op_sel_hi:[1,0]
	v_pk_mul_f32 v[96:97], v[148:149], v[96:97]
	v_pk_mul_f32 v[92:93], v[92:93], v[104:105]
	v_pk_mul_f32 v[100:101], v[90:91], v[100:101]
	v_pk_mul_f32 v[90:91], v[88:89], v[96:97]
	v_cvt_pk_bf16_f32 v88, v92, v93
	v_lshl_add_u64 v[92:93], s[38:39], 0, v[98:99]
	v_lshl_add_u64 v[92:93], v[174:175], 1, v[92:93]
	s_and_b64 vcc, exec, s[10:11]
	v_pk_mul_f32 v[94:95], v[94:95], v[102:103]
	s_nop 0
	v_cvt_pk_bf16_f32 v89, v94, v95
	v_cvt_pk_bf16_f32 v90, v90, v91
	v_cvt_pk_bf16_f32 v91, v100, v101
	global_store_dwordx4 v[92:93], v[88:91], off
	s_cbranch_vccnz .LBB0_676
	s_add_i32 s4, 0, 0x20000
	v_add_u32_e32 v88, s4, v193
	ds_read_b128 v[88:91], v88 offset:16
	s_waitcnt lgkmcnt(0)
	v_mov_b32_e32 v92, v89
	v_mov_b32_e32 v93, v90
	v_mov_b32_e32 v89, v91
	v_pk_add_f32 v[88:89], v[92:93], v[88:89]
	s_nop 0
	v_add_f32_e32 v88, v88, v89
	v_fmamk_f32 v88, v88, 0x3c000000, v208
	s_nop 1
	s_nop 0
	s_nop 1
	s_nop 1
	s_nop 1
	s_nop 0
	v_rsq_f32_e32 v88, v88
	s_nop 0
	v_mul_f32_e32 v154, v154, v88
.LBB0_676:
	s_nop 0
	v_pk_mul_f32 v[88:89], v[134:135], v[154:155] op_sel_hi:[1,0]
	v_mov_b32_e32 v155, v154
	v_pk_mul_f32 v[90:91], v[132:133], v[154:155]
	v_pk_mul_f32 v[92:93], v[140:141], v[154:155] op_sel_hi:[1,0]
	v_pk_mul_f32 v[94:95], v[138:139], v[154:155]
	v_pk_mul_f32 v[84:85], v[84:85], v[90:91]
	v_pk_mul_f32 v[86:87], v[86:87], v[88:89]
	v_pk_mul_f32 v[88:89], v[82:83], v[92:93]
	v_pk_mul_f32 v[82:83], v[80:81], v[94:95]
	v_cvt_pk_bf16_f32 v80, v84, v85
	v_lshl_add_u64 v[84:85], s[46:47], 0, v[98:99]
	v_cvt_pk_bf16_f32 v81, v86, v87
	v_cvt_pk_bf16_f32 v82, v82, v83
	v_cvt_pk_bf16_f32 v83, v88, v89
	v_lshl_add_u64 v[84:85], v[174:175], 1, v[84:85]
	global_store_dwordx4 v[84:85], v[80:83], off
	s_and_b64 vcc, exec, s[12:13]
	v_mov_b32_e32 v84, v152
	v_mov_b64_e32 v[80:81], v[152:153]
	v_mov_b64_e32 v[82:83], v[154:155]
	s_cbranch_vccnz .LBB0_678
	v_add_u32_e32 v80, 0, v195
	v_add_u32_e32 v80, 0x20000, v80
	ds_read_b128 v[80:83], v80
	s_waitcnt lgkmcnt(0)
	v_mov_b32_e32 v84, v81
	v_mov_b32_e32 v85, v82
	v_mov_b32_e32 v81, v83
	v_pk_add_f32 v[80:81], v[84:85], v[80:81]
	s_nop 0
	v_add_f32_e32 v80, v80, v81
	v_fmamk_f32 v80, v80, 0x3c000000, v208
	s_nop 1
	s_nop 0
	s_nop 1
	s_nop 1
	s_nop 1
	s_nop 0
	v_rsq_f32_e32 v80, v80
	s_nop 0
	v_mul_f32_e32 v80, v152, v80
	v_mov_b32_e32 v84, v80
.LBB0_678:
	v_add_u32_e32 v82, s36, v194
	v_mov_b32_e32 v81, v84
	v_ashrrev_i32_e32 v83, 31, v82
	v_pk_mul_f32 v[88:89], v[144:145], v[80:81]
	v_lshlrev_b64 v[82:83], 8, v[82:83]
	v_pk_mul_f32 v[86:87], v[146:147], v[84:85] op_sel_hi:[1,0]
	v_pk_mul_f32 v[84:85], v[150:151], v[84:85] op_sel_hi:[1,0]
	v_pk_mul_f32 v[80:81], v[148:149], v[80:81]
	v_pk_mul_f32 v[76:77], v[76:77], v[88:89]
	v_pk_mul_f32 v[84:85], v[74:75], v[84:85]
	v_pk_mul_f32 v[74:75], v[72:73], v[80:81]
	v_cvt_pk_bf16_f32 v72, v76, v77
	v_lshl_add_u64 v[76:77], s[38:39], 0, v[82:83]
	v_lshl_add_u64 v[76:77], v[174:175], 1, v[76:77]
	s_and_b64 vcc, exec, s[10:11]
	v_pk_mul_f32 v[78:79], v[78:79], v[86:87]
	s_nop 0
	v_cvt_pk_bf16_f32 v73, v78, v79
	v_cvt_pk_bf16_f32 v74, v74, v75
	v_cvt_pk_bf16_f32 v75, v84, v85
	global_store_dwordx4 v[76:77], v[72:75], off
	s_cbranch_vccnz .LBB0_680
	s_add_i32 s4, 0, 0x20000
	v_add_u32_e32 v72, s4, v195
	ds_read_b128 v[72:75], v72 offset:16
	s_waitcnt lgkmcnt(0)
	v_mov_b32_e32 v76, v73
	v_mov_b32_e32 v77, v74
	v_mov_b32_e32 v73, v75
	v_pk_add_f32 v[72:73], v[76:77], v[72:73]
	s_nop 0
	v_add_f32_e32 v72, v72, v73
	v_fmamk_f32 v72, v72, 0x3c000000, v208
	s_nop 1
	s_nop 0
	s_nop 1
	s_nop 1
	s_nop 1
	s_nop 0
	v_rsq_f32_e32 v72, v72
	s_nop 0
	v_mul_f32_e32 v152, v152, v72
.LBB0_680:
	s_nop 0
	v_pk_mul_f32 v[72:73], v[134:135], v[152:153] op_sel_hi:[1,0]
	v_mov_b32_e32 v153, v152
	v_pk_mul_f32 v[74:75], v[132:133], v[152:153]
	v_pk_mul_f32 v[76:77], v[140:141], v[152:153] op_sel_hi:[1,0]
	v_pk_mul_f32 v[78:79], v[138:139], v[152:153]
	v_pk_mul_f32 v[68:69], v[68:69], v[74:75]
	v_pk_mul_f32 v[70:71], v[70:71], v[72:73]
	v_pk_mul_f32 v[72:73], v[66:67], v[76:77]
	v_pk_mul_f32 v[66:67], v[64:65], v[78:79]
	v_cvt_pk_bf16_f32 v64, v68, v69
	v_lshl_add_u64 v[68:69], s[46:47], 0, v[82:83]
	v_cvt_pk_bf16_f32 v65, v70, v71
	v_cvt_pk_bf16_f32 v66, v66, v67
	v_cvt_pk_bf16_f32 v67, v72, v73
	v_lshl_add_u64 v[68:69], v[174:175], 1, v[68:69]
	global_store_dwordx4 v[68:69], v[64:67], off
	s_and_b64 vcc, exec, s[12:13]
	v_mov_b32_e32 v68, v142
	v_mov_b64_e32 v[64:65], v[142:143]
	v_mov_b64_e32 v[66:67], v[144:145]
	s_cbranch_vccnz .LBB0_682
	v_add_u32_e32 v64, 0, v197
	v_add_u32_e32 v64, 0x20000, v64
	ds_read_b128 v[64:67], v64
	s_waitcnt lgkmcnt(0)
	v_mov_b32_e32 v68, v65
	v_mov_b32_e32 v69, v66
	v_mov_b32_e32 v65, v67
	v_pk_add_f32 v[64:65], v[68:69], v[64:65]
	s_nop 0
	v_add_f32_e32 v64, v64, v65
	v_fmamk_f32 v64, v64, 0x3c000000, v208
	s_nop 1
	s_nop 0
	s_nop 1
	s_nop 1
	s_nop 1
	s_nop 0
	v_rsq_f32_e32 v64, v64
	s_nop 0
	v_mul_f32_e32 v64, v142, v64
	v_mov_b32_e32 v68, v64
.LBB0_682:
	v_add_u32_e32 v66, s36, v196
	v_mov_b32_e32 v65, v68
	v_ashrrev_i32_e32 v67, 31, v66
	v_pk_mul_f32 v[72:73], v[144:145], v[64:65]
	v_lshlrev_b64 v[66:67], 8, v[66:67]
	v_pk_mul_f32 v[70:71], v[146:147], v[68:69] op_sel_hi:[1,0]
	v_pk_mul_f32 v[68:69], v[150:151], v[68:69] op_sel_hi:[1,0]
	v_pk_mul_f32 v[64:65], v[148:149], v[64:65]
	v_pk_mul_f32 v[60:61], v[60:61], v[72:73]
	v_pk_mul_f32 v[68:69], v[58:59], v[68:69]
	v_pk_mul_f32 v[58:59], v[56:57], v[64:65]
	v_cvt_pk_bf16_f32 v56, v60, v61
	v_lshl_add_u64 v[60:61], s[38:39], 0, v[66:67]
	v_lshl_add_u64 v[60:61], v[174:175], 1, v[60:61]
	s_and_b64 vcc, exec, s[10:11]
	v_pk_mul_f32 v[62:63], v[62:63], v[70:71]
	s_nop 0
	v_cvt_pk_bf16_f32 v57, v62, v63
	v_cvt_pk_bf16_f32 v58, v58, v59
	v_cvt_pk_bf16_f32 v59, v68, v69
	global_store_dwordx4 v[60:61], v[56:59], off
	s_cbranch_vccnz .LBB0_684
	s_add_i32 s4, 0, 0x20000
	v_add_u32_e32 v56, s4, v197
	ds_read_b128 v[56:59], v56 offset:16
	s_waitcnt lgkmcnt(0)
	v_mov_b32_e32 v60, v57
	v_mov_b32_e32 v61, v58
	v_mov_b32_e32 v57, v59
	v_pk_add_f32 v[56:57], v[60:61], v[56:57]
	s_nop 0
	v_add_f32_e32 v56, v56, v57
	v_fmamk_f32 v56, v56, 0x3c000000, v208
	s_nop 1
	s_nop 0
	s_nop 1
	s_nop 1
	s_nop 1
	s_nop 0
	v_rsq_f32_e32 v56, v56
	s_nop 0
	v_mul_f32_e32 v142, v142, v56
.LBB0_684:
	s_nop 0
	v_pk_mul_f32 v[56:57], v[134:135], v[142:143] op_sel_hi:[1,0]
	v_mov_b32_e32 v143, v142
	v_pk_mul_f32 v[58:59], v[132:133], v[142:143]
	v_pk_mul_f32 v[60:61], v[140:141], v[142:143] op_sel_hi:[1,0]
	v_pk_mul_f32 v[62:63], v[138:139], v[142:143]
	v_pk_mul_f32 v[52:53], v[52:53], v[58:59]
	v_pk_mul_f32 v[54:55], v[54:55], v[56:57]
	v_pk_mul_f32 v[56:57], v[50:51], v[60:61]
	v_pk_mul_f32 v[50:51], v[48:49], v[62:63]
	v_cvt_pk_bf16_f32 v48, v52, v53
	v_lshl_add_u64 v[52:53], s[46:47], 0, v[66:67]
	v_cvt_pk_bf16_f32 v49, v54, v55
	v_cvt_pk_bf16_f32 v50, v50, v51
	v_cvt_pk_bf16_f32 v51, v56, v57
	v_lshl_add_u64 v[52:53], v[174:175], 1, v[52:53]
	global_store_dwordx4 v[52:53], v[48:51], off
	s_and_b64 vcc, exec, s[12:13]
	v_mov_b32_e32 v52, v136
	v_mov_b64_e32 v[48:49], v[136:137]
	v_mov_b64_e32 v[50:51], v[138:139]
	s_cbranch_vccnz .LBB0_686
	v_add_u32_e32 v48, 0, v199
	v_add_u32_e32 v48, 0x20000, v48
	ds_read_b128 v[48:51], v48
	s_waitcnt lgkmcnt(0)
	v_mov_b32_e32 v52, v49
	v_mov_b32_e32 v53, v50
	v_mov_b32_e32 v49, v51
	v_pk_add_f32 v[48:49], v[52:53], v[48:49]
	s_nop 0
	v_add_f32_e32 v48, v48, v49
	v_fmamk_f32 v48, v48, 0x3c000000, v208
	s_nop 1
	s_nop 0
	s_nop 1
	s_nop 1
	s_nop 1
	s_nop 0
	v_rsq_f32_e32 v48, v48
	s_nop 0
	v_mul_f32_e32 v48, v136, v48
	v_mov_b32_e32 v52, v48
.LBB0_686:
	v_add_u32_e32 v50, s36, v198
	v_mov_b32_e32 v49, v52
	v_ashrrev_i32_e32 v51, 31, v50
	v_pk_mul_f32 v[56:57], v[144:145], v[48:49]
	v_lshlrev_b64 v[50:51], 8, v[50:51]
	v_pk_mul_f32 v[54:55], v[146:147], v[52:53] op_sel_hi:[1,0]
	v_pk_mul_f32 v[52:53], v[150:151], v[52:53] op_sel_hi:[1,0]
	v_pk_mul_f32 v[48:49], v[148:149], v[48:49]
	v_pk_mul_f32 v[44:45], v[44:45], v[56:57]
	v_pk_mul_f32 v[52:53], v[42:43], v[52:53]
	v_pk_mul_f32 v[42:43], v[40:41], v[48:49]
	v_cvt_pk_bf16_f32 v40, v44, v45
	v_lshl_add_u64 v[44:45], s[38:39], 0, v[50:51]
	v_lshl_add_u64 v[44:45], v[174:175], 1, v[44:45]
	s_and_b64 vcc, exec, s[10:11]
	v_pk_mul_f32 v[46:47], v[46:47], v[54:55]
	s_nop 0
	v_cvt_pk_bf16_f32 v41, v46, v47
	v_cvt_pk_bf16_f32 v42, v42, v43
	v_cvt_pk_bf16_f32 v43, v52, v53
	global_store_dwordx4 v[44:45], v[40:43], off
	s_cbranch_vccnz .LBB0_688
	s_add_i32 s4, 0, 0x20000
	v_add_u32_e32 v40, s4, v199
	ds_read_b128 v[40:43], v40 offset:16
	s_waitcnt lgkmcnt(0)
	v_mov_b32_e32 v44, v41
	v_mov_b32_e32 v45, v42
	v_mov_b32_e32 v41, v43
	v_pk_add_f32 v[40:41], v[44:45], v[40:41]
	s_nop 0
	v_add_f32_e32 v40, v40, v41
	v_fmamk_f32 v40, v40, 0x3c000000, v208
	s_nop 1
	s_nop 0
	s_nop 1
	s_nop 1
	s_nop 1
	s_nop 0
	v_rsq_f32_e32 v40, v40
	s_nop 0
	v_mul_f32_e32 v136, v136, v40
.LBB0_688:
	s_nop 0
	v_pk_mul_f32 v[40:41], v[134:135], v[136:137] op_sel_hi:[1,0]
	v_mov_b32_e32 v137, v136
	v_pk_mul_f32 v[42:43], v[132:133], v[136:137]
	v_pk_mul_f32 v[44:45], v[140:141], v[136:137] op_sel_hi:[1,0]
	v_pk_mul_f32 v[46:47], v[138:139], v[136:137]
	v_pk_mul_f32 v[36:37], v[36:37], v[42:43]
	v_pk_mul_f32 v[38:39], v[38:39], v[40:41]
	v_pk_mul_f32 v[40:41], v[34:35], v[44:45]
	v_pk_mul_f32 v[34:35], v[32:33], v[46:47]
	v_cvt_pk_bf16_f32 v32, v36, v37
	v_lshl_add_u64 v[36:37], s[46:47], 0, v[50:51]
	v_cvt_pk_bf16_f32 v33, v38, v39
	v_cvt_pk_bf16_f32 v34, v34, v35
	v_cvt_pk_bf16_f32 v35, v40, v41
	v_lshl_add_u64 v[36:37], v[174:175], 1, v[36:37]
	global_store_dwordx4 v[36:37], v[32:35], off
	s_and_b64 vcc, exec, s[12:13]
	v_mov_b32_e32 v36, v130
	v_mov_b64_e32 v[32:33], v[130:131]
	v_mov_b64_e32 v[34:35], v[132:133]
	s_cbranch_vccnz .LBB0_690
	v_add_u32_e32 v32, 0, v201
	v_add_u32_e32 v32, 0x20000, v32
	ds_read_b128 v[32:35], v32
	s_waitcnt lgkmcnt(0)
	v_mov_b32_e32 v36, v33
	v_mov_b32_e32 v37, v34
	v_mov_b32_e32 v33, v35
	v_pk_add_f32 v[32:33], v[36:37], v[32:33]
	s_nop 0
	v_add_f32_e32 v32, v32, v33
	v_fmamk_f32 v32, v32, 0x3c000000, v208
	s_nop 1
	s_nop 0
	s_nop 1
	s_nop 1
	s_nop 1
	s_nop 0
	v_rsq_f32_e32 v32, v32
	s_nop 0
	v_mul_f32_e32 v32, v130, v32
	v_mov_b32_e32 v36, v32
.LBB0_690:
	v_add_u32_e32 v34, s36, v200
	v_mov_b32_e32 v33, v36
	v_ashrrev_i32_e32 v35, 31, v34
	v_pk_mul_f32 v[40:41], v[144:145], v[32:33]
	v_lshlrev_b64 v[34:35], 8, v[34:35]
	v_pk_mul_f32 v[38:39], v[146:147], v[36:37] op_sel_hi:[1,0]
	v_pk_mul_f32 v[36:37], v[150:151], v[36:37] op_sel_hi:[1,0]
	v_pk_mul_f32 v[32:33], v[148:149], v[32:33]
	v_pk_mul_f32 v[28:29], v[28:29], v[40:41]
	v_pk_mul_f32 v[36:37], v[26:27], v[36:37]
	v_pk_mul_f32 v[26:27], v[24:25], v[32:33]
	v_cvt_pk_bf16_f32 v24, v28, v29
	v_lshl_add_u64 v[28:29], s[38:39], 0, v[34:35]
	v_lshl_add_u64 v[28:29], v[174:175], 1, v[28:29]
	s_and_b64 vcc, exec, s[10:11]
	v_pk_mul_f32 v[30:31], v[30:31], v[38:39]
	s_nop 0
	v_cvt_pk_bf16_f32 v25, v30, v31
	v_cvt_pk_bf16_f32 v26, v26, v27
	v_cvt_pk_bf16_f32 v27, v36, v37
	global_store_dwordx4 v[28:29], v[24:27], off
	s_cbranch_vccnz .LBB0_692
	s_add_i32 s4, 0, 0x20000
	v_add_u32_e32 v24, s4, v201
	ds_read_b128 v[24:27], v24 offset:16
	s_waitcnt lgkmcnt(0)
	v_mov_b32_e32 v28, v25
	v_mov_b32_e32 v29, v26
	v_mov_b32_e32 v25, v27
	v_pk_add_f32 v[24:25], v[28:29], v[24:25]
	s_nop 0
	v_add_f32_e32 v24, v24, v25
	v_fmamk_f32 v24, v24, 0x3c000000, v208
	s_nop 1
	s_nop 0
	s_nop 1
	s_nop 1
	s_nop 1
	s_nop 0
	v_rsq_f32_e32 v24, v24
	s_nop 0
	v_mul_f32_e32 v130, v130, v24
.LBB0_692:
	s_nop 0
	v_pk_mul_f32 v[24:25], v[134:135], v[130:131] op_sel_hi:[1,0]
	v_mov_b32_e32 v131, v130
	v_pk_mul_f32 v[26:27], v[132:133], v[130:131]
	v_pk_mul_f32 v[28:29], v[140:141], v[130:131] op_sel_hi:[1,0]
	v_pk_mul_f32 v[30:31], v[138:139], v[130:131]
	v_pk_mul_f32 v[20:21], v[20:21], v[26:27]
	v_pk_mul_f32 v[22:23], v[22:23], v[24:25]
	v_pk_mul_f32 v[24:25], v[18:19], v[28:29]
	v_pk_mul_f32 v[18:19], v[16:17], v[30:31]
	v_cvt_pk_bf16_f32 v16, v20, v21
	v_lshl_add_u64 v[20:21], s[46:47], 0, v[34:35]
	v_cvt_pk_bf16_f32 v17, v22, v23
	v_cvt_pk_bf16_f32 v18, v18, v19
	v_cvt_pk_bf16_f32 v19, v24, v25
	v_lshl_add_u64 v[20:21], v[174:175], 1, v[20:21]
	global_store_dwordx4 v[20:21], v[16:19], off
	s_and_b64 vcc, exec, s[12:13]
	v_mov_b32_e32 v20, v128
	v_mov_b64_e32 v[16:17], v[128:129]
	v_mov_b64_e32 v[18:19], v[130:131]
	s_cbranch_vccnz .LBB0_694
	v_add_u32_e32 v16, 0, v203
	v_add_u32_e32 v16, 0x20000, v16
	ds_read_b128 v[16:19], v16
	s_waitcnt lgkmcnt(0)
	v_mov_b32_e32 v20, v17
	v_mov_b32_e32 v21, v18
	v_mov_b32_e32 v17, v19
	v_pk_add_f32 v[16:17], v[20:21], v[16:17]
	s_nop 0
	v_add_f32_e32 v16, v16, v17
	v_fmamk_f32 v16, v16, 0x3c000000, v208
	s_nop 1
	s_nop 0
	s_nop 1
	s_nop 1
	s_nop 1
	s_nop 0
	v_rsq_f32_e32 v16, v16
	s_nop 0
	v_mul_f32_e32 v16, v128, v16
	v_mov_b32_e32 v20, v16
.LBB0_694:
	v_add_u32_e32 v18, s36, v202
	v_mov_b32_e32 v17, v20
	v_ashrrev_i32_e32 v19, 31, v18
	v_pk_mul_f32 v[24:25], v[144:145], v[16:17]
	v_lshlrev_b64 v[18:19], 8, v[18:19]
	v_pk_mul_f32 v[22:23], v[146:147], v[20:21] op_sel_hi:[1,0]
	v_pk_mul_f32 v[20:21], v[150:151], v[20:21] op_sel_hi:[1,0]
	v_pk_mul_f32 v[16:17], v[148:149], v[16:17]
	v_pk_mul_f32 v[12:13], v[12:13], v[24:25]
	v_pk_mul_f32 v[20:21], v[10:11], v[20:21]
	v_pk_mul_f32 v[10:11], v[8:9], v[16:17]
	v_cvt_pk_bf16_f32 v8, v12, v13
	v_lshl_add_u64 v[12:13], s[38:39], 0, v[18:19]
	v_lshl_add_u64 v[12:13], v[174:175], 1, v[12:13]
	s_and_b64 vcc, exec, s[10:11]
	v_pk_mul_f32 v[14:15], v[14:15], v[22:23]
	s_nop 0
	v_cvt_pk_bf16_f32 v9, v14, v15
	v_cvt_pk_bf16_f32 v10, v10, v11
	v_cvt_pk_bf16_f32 v11, v20, v21
	global_store_dwordx4 v[12:13], v[8:11], off
	s_cbranch_vccnz .LBB0_696
	s_add_i32 s4, 0, 0x20000
	v_add_u32_e32 v8, s4, v203
	ds_read_b128 v[8:11], v8 offset:16
	s_waitcnt lgkmcnt(0)
	v_mov_b32_e32 v12, v9
	v_mov_b32_e32 v13, v10
	v_mov_b32_e32 v9, v11
	v_pk_add_f32 v[8:9], v[12:13], v[8:9]
	s_nop 0
	v_add_f32_e32 v8, v8, v9
	v_fmamk_f32 v8, v8, 0x3c000000, v208
	s_nop 1
	s_nop 0
	s_nop 1
	s_nop 1
	s_nop 1
	s_nop 0
	v_rsq_f32_e32 v8, v8
	s_nop 0
	v_mul_f32_e32 v128, v128, v8

.LBB0_1413:
	v_lshl_add_u32 v144, s8, 8, v152
	v_ashrrev_i32_e32 v145, 31, v144
	v_lshl_add_u64 v[150:151], v[144:145], 2, s[10:11]
	global_load_dword v145, v[150:151], off
	v_lshl_add_u32 v146, s9, 7, v154
	v_or_b32_e32 v162, 16, v144
	v_mov_b64_e32 v[148:149], s[12:13]
	v_ashrrev_i32_e32 v147, 31, v146
	v_mad_i64_i32 v[160:161], s[4:5], v144, s42, v[148:149]
	v_lshlrev_b64 v[146:147], 1, v[146:147]
	v_lshl_add_u64 v[160:161], v[160:161], 0, v[146:147]
	s_waitcnt vmcnt(0) lgkmcnt(0)
	v_fmamk_f32 v145, v145, 0x3a000000, v158
	s_nop 1
	v_ashrrev_i32_e32 v163, 31, v162
	s_nop 1
	s_nop 1
	s_nop 1
	v_lshl_add_u64 v[164:165], v[162:163], 2, s[10:11]
	v_rsq_f32_e32 v166, v145
	s_nop 0
	v_pk_mul_f32 v[126:127], v[126:127], v[166:167] op_sel_hi:[1,0]
	v_pk_mul_f32 v[124:125], v[124:125], v[166:167] op_sel_hi:[1,0]
	v_pk_mul_f32 v[122:123], v[122:123], v[166:167] op_sel_hi:[1,0]
	v_pk_mul_f32 v[120:121], v[120:121], v[166:167] op_sel_hi:[1,0]
	v_pk_mul_f32 v[116:117], v[116:117], v[166:167] op_sel_hi:[1,0]
	v_pk_mul_f32 v[118:119], v[118:119], v[166:167] op_sel_hi:[1,0]
	v_pk_mul_f32 v[112:113], v[112:113], v[166:167] op_sel_hi:[1,0]
	v_pk_mul_f32 v[114:115], v[114:115], v[166:167] op_sel_hi:[1,0]
	v_pk_mul_f32 v[166:167], v[124:125], s[18:19] op_sel_hi:[1,0]
	v_pk_mul_f32 v[118:119], v[126:127], v[118:119]
	v_pk_mul_f32 v[116:117], v[124:125], v[116:117]
	v_pk_mul_f32 v[124:125], v[126:127], s[18:19] op_sel_hi:[1,0]
	v_pk_mul_f32 v[126:127], v[120:121], s[18:19] op_sel_hi:[1,0]
	v_pk_mul_f32 v[112:113], v[120:121], v[112:113]
	v_pk_mul_f32 v[120:121], v[122:123], s[18:19] op_sel_hi:[1,0]
	v_pk_mul_f32 v[114:115], v[122:123], v[114:115]
	v_exp_f32_e32 v122, v166
	v_exp_f32_e32 v123, v167
	v_exp_f32_e32 v124, v124
	v_exp_f32_e32 v125, v125
	v_exp_f32_e32 v126, v126
	v_exp_f32_e32 v127, v127
	v_exp_f32_e32 v120, v120
	v_exp_f32_e32 v121, v121
	v_pk_add_f32 v[122:123], v[122:123], 1.0 op_sel_hi:[1,0]
	v_pk_add_f32 v[124:125], v[124:125], 1.0 op_sel_hi:[1,0]
	v_pk_add_f32 v[126:127], v[126:127], 1.0 op_sel_hi:[1,0]
	v_pk_add_f32 v[120:121], v[120:121], 1.0 op_sel_hi:[1,0]
	v_rcp_f32_e32 v122, v122
	v_rcp_f32_e32 v123, v123
	v_rcp_f32_e32 v124, v124
	v_rcp_f32_e32 v125, v125
	v_rcp_f32_e32 v126, v126
	v_rcp_f32_e32 v127, v127
	v_rcp_f32_e32 v120, v120
	v_rcp_f32_e32 v121, v121
	v_pk_mul_f32 v[116:117], v[116:117], v[122:123]
	v_pk_mul_f32 v[118:119], v[118:119], v[124:125]
	v_pk_mul_f32 v[122:123], v[112:113], v[126:127]
	v_pk_mul_f32 v[120:121], v[114:115], v[120:121]
	v_cvt_pk_bf16_f32 v112, v116, v117
	v_cvt_pk_bf16_f32 v113, v118, v119
	v_cvt_pk_bf16_f32 v114, v122, v123
	s_nop 0
	v_cvt_pk_bf16_f32 v115, v120, v121
	global_store_dwordx4 v[160:161], v[112:115], off
	global_load_dword v113, v[164:165], off
	s_nop 0
	v_or_b32_e32 v112, 32, v144
	s_waitcnt vmcnt(0) lgkmcnt(0)
	v_fmamk_f32 v113, v113, 0x3a000000, v158
	v_rsq_f32_e32 v118, v113
	s_nop 1
	v_ashrrev_i32_e32 v113, 31, v112
	v_mad_i64_i32 v[114:115], s[4:5], v162, s42, v[148:149]
	v_lshl_add_u64 v[114:115], v[114:115], 0, v[146:147]
	s_nop 0
	s_nop 1
	s_nop 1
	v_lshl_add_u64 v[116:117], v[112:113], 2, s[10:11]
	s_nop 0
	v_pk_mul_f32 v[110:111], v[110:111], v[118:119] op_sel_hi:[1,0]
	v_pk_mul_f32 v[108:109], v[108:109], v[118:119] op_sel_hi:[1,0]
	v_pk_mul_f32 v[106:107], v[106:107], v[118:119] op_sel_hi:[1,0]
	v_pk_mul_f32 v[104:105], v[104:105], v[118:119] op_sel_hi:[1,0]
	v_pk_mul_f32 v[100:101], v[100:101], v[118:119] op_sel_hi:[1,0]
	v_pk_mul_f32 v[102:103], v[102:103], v[118:119] op_sel_hi:[1,0]
	v_pk_mul_f32 v[96:97], v[96:97], v[118:119] op_sel_hi:[1,0]
	v_pk_mul_f32 v[98:99], v[98:99], v[118:119] op_sel_hi:[1,0]
	v_pk_mul_f32 v[118:119], v[108:109], s[18:19] op_sel_hi:[1,0]
	v_pk_mul_f32 v[102:103], v[110:111], v[102:103]
	v_pk_mul_f32 v[100:101], v[108:109], v[100:101]
	v_pk_mul_f32 v[108:109], v[110:111], s[18:19] op_sel_hi:[1,0]
	v_pk_mul_f32 v[110:111], v[104:105], s[18:19] op_sel_hi:[1,0]
	v_pk_mul_f32 v[96:97], v[104:105], v[96:97]
	v_pk_mul_f32 v[104:105], v[106:107], s[18:19] op_sel_hi:[1,0]
	v_pk_mul_f32 v[98:99], v[106:107], v[98:99]
	v_exp_f32_e32 v106, v118
	v_exp_f32_e32 v107, v119
	v_exp_f32_e32 v108, v108
	v_exp_f32_e32 v109, v109
	v_exp_f32_e32 v110, v110
	v_exp_f32_e32 v111, v111
	v_exp_f32_e32 v104, v104
	v_exp_f32_e32 v105, v105
	v_pk_add_f32 v[106:107], v[106:107], 1.0 op_sel_hi:[1,0]
	v_pk_add_f32 v[108:109], v[108:109], 1.0 op_sel_hi:[1,0]
	v_pk_add_f32 v[110:111], v[110:111], 1.0 op_sel_hi:[1,0]
	v_pk_add_f32 v[104:105], v[104:105], 1.0 op_sel_hi:[1,0]
	v_rcp_f32_e32 v106, v106
	v_rcp_f32_e32 v107, v107
	v_rcp_f32_e32 v108, v108
	v_rcp_f32_e32 v109, v109
	v_rcp_f32_e32 v110, v110
	v_rcp_f32_e32 v111, v111
	v_rcp_f32_e32 v104, v104
	v_rcp_f32_e32 v105, v105
	v_pk_mul_f32 v[100:101], v[100:101], v[106:107]
	v_pk_mul_f32 v[102:103], v[102:103], v[108:109]
	v_pk_mul_f32 v[106:107], v[96:97], v[110:111]
	v_pk_mul_f32 v[104:105], v[98:99], v[104:105]
	v_cvt_pk_bf16_f32 v96, v100, v101
	v_cvt_pk_bf16_f32 v97, v102, v103
	v_cvt_pk_bf16_f32 v98, v106, v107
	s_nop 0
	v_cvt_pk_bf16_f32 v99, v104, v105
	global_store_dwordx4 v[114:115], v[96:99], off
	global_load_dword v97, v[116:117], off
	s_nop 0
	v_or_b32_e32 v96, 48, v144
	s_waitcnt vmcnt(0) lgkmcnt(0)
	v_fmamk_f32 v97, v97, 0x3a000000, v158
	v_rsq_f32_e32 v102, v97
	s_nop 1
	v_ashrrev_i32_e32 v97, 31, v96
	v_mad_i64_i32 v[98:99], s[4:5], v112, s42, v[148:149]
	v_lshl_add_u64 v[98:99], v[98:99], 0, v[146:147]
	s_nop 0
	s_nop 1
	s_nop 1
	v_lshl_add_u64 v[100:101], v[96:97], 2, s[10:11]
	s_nop 0
	v_pk_mul_f32 v[94:95], v[94:95], v[102:103] op_sel_hi:[1,0]
	v_pk_mul_f32 v[92:93], v[92:93], v[102:103] op_sel_hi:[1,0]
	v_pk_mul_f32 v[90:91], v[90:91], v[102:103] op_sel_hi:[1,0]
	v_pk_mul_f32 v[88:89], v[88:89], v[102:103] op_sel_hi:[1,0]
	v_pk_mul_f32 v[84:85], v[84:85], v[102:103] op_sel_hi:[1,0]
	v_pk_mul_f32 v[86:87], v[86:87], v[102:103] op_sel_hi:[1,0]
	v_pk_mul_f32 v[80:81], v[80:81], v[102:103] op_sel_hi:[1,0]
	v_pk_mul_f32 v[82:83], v[82:83], v[102:103] op_sel_hi:[1,0]
	v_pk_mul_f32 v[102:103], v[92:93], s[18:19] op_sel_hi:[1,0]
	v_pk_mul_f32 v[86:87], v[94:95], v[86:87]
	v_pk_mul_f32 v[84:85], v[92:93], v[84:85]
	v_pk_mul_f32 v[92:93], v[94:95], s[18:19] op_sel_hi:[1,0]
	v_pk_mul_f32 v[94:95], v[88:89], s[18:19] op_sel_hi:[1,0]
	v_pk_mul_f32 v[80:81], v[88:89], v[80:81]
	v_pk_mul_f32 v[88:89], v[90:91], s[18:19] op_sel_hi:[1,0]
	v_pk_mul_f32 v[82:83], v[90:91], v[82:83]
	v_exp_f32_e32 v90, v102
	v_exp_f32_e32 v91, v103
	v_exp_f32_e32 v92, v92
	v_exp_f32_e32 v93, v93
	v_exp_f32_e32 v94, v94
	v_exp_f32_e32 v95, v95
	v_exp_f32_e32 v88, v88
	v_exp_f32_e32 v89, v89
	v_pk_add_f32 v[90:91], v[90:91], 1.0 op_sel_hi:[1,0]
	v_pk_add_f32 v[92:93], v[92:93], 1.0 op_sel_hi:[1,0]
	v_pk_add_f32 v[94:95], v[94:95], 1.0 op_sel_hi:[1,0]
	v_pk_add_f32 v[88:89], v[88:89], 1.0 op_sel_hi:[1,0]
	v_rcp_f32_e32 v90, v90
	v_rcp_f32_e32 v91, v91
	v_rcp_f32_e32 v92, v92
	v_rcp_f32_e32 v93, v93
	v_rcp_f32_e32 v94, v94
	v_rcp_f32_e32 v95, v95
	v_rcp_f32_e32 v88, v88
	v_rcp_f32_e32 v89, v89
	v_pk_mul_f32 v[84:85], v[84:85], v[90:91]
	v_pk_mul_f32 v[86:87], v[86:87], v[92:93]
	v_pk_mul_f32 v[90:91], v[80:81], v[94:95]
	v_pk_mul_f32 v[88:89], v[82:83], v[88:89]
	v_cvt_pk_bf16_f32 v80, v84, v85
	v_cvt_pk_bf16_f32 v81, v86, v87
	v_cvt_pk_bf16_f32 v82, v90, v91
	s_nop 0
	v_cvt_pk_bf16_f32 v83, v88, v89
	global_store_dwordx4 v[98:99], v[80:83], off
	global_load_dword v80, v[100:101], off
	s_waitcnt vmcnt(0) lgkmcnt(0)
	v_fmamk_f32 v80, v80, 0x3a000000, v158
	v_rsq_f32_e32 v82, v80
	s_nop 1
	v_mad_i64_i32 v[80:81], s[4:5], v96, s42, v[148:149]
	v_lshl_add_u64 v[80:81], v[80:81], 0, v[146:147]
	s_nop 1
	s_nop 1
	s_nop 1
	s_nop 0
	v_pk_mul_f32 v[78:79], v[78:79], v[82:83] op_sel_hi:[1,0]
	v_pk_mul_f32 v[76:77], v[76:77], v[82:83] op_sel_hi:[1,0]
	v_pk_mul_f32 v[74:75], v[74:75], v[82:83] op_sel_hi:[1,0]
	v_pk_mul_f32 v[72:73], v[72:73], v[82:83] op_sel_hi:[1,0]
	v_pk_mul_f32 v[68:69], v[68:69], v[82:83] op_sel_hi:[1,0]
	v_pk_mul_f32 v[70:71], v[70:71], v[82:83] op_sel_hi:[1,0]
	v_pk_mul_f32 v[64:65], v[64:65], v[82:83] op_sel_hi:[1,0]
	v_pk_mul_f32 v[66:67], v[66:67], v[82:83] op_sel_hi:[1,0]
	v_pk_mul_f32 v[82:83], v[76:77], s[18:19] op_sel_hi:[1,0]
	v_pk_mul_f32 v[70:71], v[78:79], v[70:71]
	v_pk_mul_f32 v[68:69], v[76:77], v[68:69]
	v_pk_mul_f32 v[76:77], v[78:79], s[18:19] op_sel_hi:[1,0]
	v_pk_mul_f32 v[78:79], v[72:73], s[18:19] op_sel_hi:[1,0]
	v_pk_mul_f32 v[64:65], v[72:73], v[64:65]
	v_pk_mul_f32 v[72:73], v[74:75], s[18:19] op_sel_hi:[1,0]
	v_pk_mul_f32 v[66:67], v[74:75], v[66:67]
	v_exp_f32_e32 v74, v82
	v_exp_f32_e32 v75, v83
	v_exp_f32_e32 v76, v76
	v_exp_f32_e32 v77, v77
	v_exp_f32_e32 v78, v78
	v_exp_f32_e32 v79, v79
	v_exp_f32_e32 v72, v72
	v_exp_f32_e32 v73, v73
	v_pk_add_f32 v[74:75], v[74:75], 1.0 op_sel_hi:[1,0]
	v_pk_add_f32 v[76:77], v[76:77], 1.0 op_sel_hi:[1,0]
	v_pk_add_f32 v[78:79], v[78:79], 1.0 op_sel_hi:[1,0]
	v_pk_add_f32 v[72:73], v[72:73], 1.0 op_sel_hi:[1,0]
	v_rcp_f32_e32 v74, v74
	v_rcp_f32_e32 v75, v75
	v_rcp_f32_e32 v76, v76
	v_rcp_f32_e32 v77, v77
	v_rcp_f32_e32 v78, v78
	v_rcp_f32_e32 v79, v79
	v_rcp_f32_e32 v72, v72
	v_rcp_f32_e32 v73, v73
	v_pk_mul_f32 v[68:69], v[68:69], v[74:75]
	v_pk_mul_f32 v[70:71], v[70:71], v[76:77]
	v_pk_mul_f32 v[74:75], v[64:65], v[78:79]
	v_pk_mul_f32 v[72:73], v[66:67], v[72:73]
	v_cvt_pk_bf16_f32 v64, v68, v69
	v_cvt_pk_bf16_f32 v65, v70, v71
	v_cvt_pk_bf16_f32 v66, v74, v75
	s_nop 0
	v_cvt_pk_bf16_f32 v67, v72, v73
	global_store_dwordx4 v[80:81], v[64:67], off
	global_load_dword v64, v[150:151], off offset:512
	s_waitcnt vmcnt(0) lgkmcnt(0)
	v_fmamk_f32 v64, v64, 0x3a000000, v158
	v_rsq_f32_e32 v66, v64
	s_nop 1
	v_add_u32_e32 v64, 0x80, v144
	v_mad_i64_i32 v[64:65], s[4:5], v64, s42, v[148:149]
	v_lshl_add_u64 v[64:65], v[64:65], 0, v[146:147]
	s_nop 0
	s_nop 1
	s_nop 1
	s_nop 0
	v_pk_mul_f32 v[62:63], v[62:63], v[66:67] op_sel_hi:[1,0]
	v_pk_mul_f32 v[60:61], v[60:61], v[66:67] op_sel_hi:[1,0]
	v_pk_mul_f32 v[58:59], v[58:59], v[66:67] op_sel_hi:[1,0]
	v_pk_mul_f32 v[56:57], v[56:57], v[66:67] op_sel_hi:[1,0]
	v_pk_mul_f32 v[52:53], v[52:53], v[66:67] op_sel_hi:[1,0]
	v_pk_mul_f32 v[54:55], v[54:55], v[66:67] op_sel_hi:[1,0]
	v_pk_mul_f32 v[48:49], v[48:49], v[66:67] op_sel_hi:[1,0]
	v_pk_mul_f32 v[50:51], v[50:51], v[66:67] op_sel_hi:[1,0]
	v_pk_mul_f32 v[66:67], v[60:61], s[18:19] op_sel_hi:[1,0]
	v_pk_mul_f32 v[54:55], v[62:63], v[54:55]
	v_pk_mul_f32 v[52:53], v[60:61], v[52:53]
	v_pk_mul_f32 v[60:61], v[62:63], s[18:19] op_sel_hi:[1,0]
	v_pk_mul_f32 v[62:63], v[56:57], s[18:19] op_sel_hi:[1,0]
	v_pk_mul_f32 v[48:49], v[56:57], v[48:49]
	v_pk_mul_f32 v[56:57], v[58:59], s[18:19] op_sel_hi:[1,0]
	v_pk_mul_f32 v[50:51], v[58:59], v[50:51]
	v_exp_f32_e32 v58, v66
	v_exp_f32_e32 v59, v67
	v_exp_f32_e32 v60, v60
	v_exp_f32_e32 v61, v61
	v_exp_f32_e32 v62, v62
	v_exp_f32_e32 v63, v63
	v_exp_f32_e32 v56, v56
	v_exp_f32_e32 v57, v57
	v_pk_add_f32 v[58:59], v[58:59], 1.0 op_sel_hi:[1,0]
	v_pk_add_f32 v[60:61], v[60:61], 1.0 op_sel_hi:[1,0]
	v_pk_add_f32 v[62:63], v[62:63], 1.0 op_sel_hi:[1,0]
	v_pk_add_f32 v[56:57], v[56:57], 1.0 op_sel_hi:[1,0]
	v_rcp_f32_e32 v58, v58
	v_rcp_f32_e32 v59, v59
	v_rcp_f32_e32 v60, v60
	v_rcp_f32_e32 v61, v61
	v_rcp_f32_e32 v62, v62
	v_rcp_f32_e32 v63, v63
	v_rcp_f32_e32 v56, v56
	v_rcp_f32_e32 v57, v57
	v_pk_mul_f32 v[52:53], v[52:53], v[58:59]
	v_pk_mul_f32 v[54:55], v[54:55], v[60:61]
	v_pk_mul_f32 v[58:59], v[48:49], v[62:63]
	v_pk_mul_f32 v[56:57], v[50:51], v[56:57]
	v_cvt_pk_bf16_f32 v48, v52, v53
	v_cvt_pk_bf16_f32 v49, v54, v55
	v_cvt_pk_bf16_f32 v50, v58, v59
	s_nop 0
	v_cvt_pk_bf16_f32 v51, v56, v57
	global_store_dwordx4 v[64:65], v[48:51], off
	global_load_dword v48, v[150:151], off offset:576
	s_waitcnt vmcnt(0) lgkmcnt(0)
	v_fmamk_f32 v48, v48, 0x3a000000, v158
	v_rsq_f32_e32 v50, v48
	s_nop 1
	v_add_u32_e32 v48, 0x90, v144
	v_mad_i64_i32 v[48:49], s[4:5], v48, s42, v[148:149]
	v_lshl_add_u64 v[48:49], v[48:49], 0, v[146:147]
	s_nop 0
	s_nop 1
	s_nop 1
	s_nop 0
	v_pk_mul_f32 v[46:47], v[46:47], v[50:51] op_sel_hi:[1,0]
	v_pk_mul_f32 v[44:45], v[44:45], v[50:51] op_sel_hi:[1,0]
	v_pk_mul_f32 v[42:43], v[42:43], v[50:51] op_sel_hi:[1,0]
	v_pk_mul_f32 v[40:41], v[40:41], v[50:51] op_sel_hi:[1,0]
	v_pk_mul_f32 v[36:37], v[36:37], v[50:51] op_sel_hi:[1,0]
	v_pk_mul_f32 v[38:39], v[38:39], v[50:51] op_sel_hi:[1,0]
	v_pk_mul_f32 v[32:33], v[32:33], v[50:51] op_sel_hi:[1,0]
	v_pk_mul_f32 v[34:35], v[34:35], v[50:51] op_sel_hi:[1,0]
	v_pk_mul_f32 v[50:51], v[44:45], s[18:19] op_sel_hi:[1,0]
	v_pk_mul_f32 v[38:39], v[46:47], v[38:39]
	v_pk_mul_f32 v[36:37], v[44:45], v[36:37]
	v_pk_mul_f32 v[44:45], v[46:47], s[18:19] op_sel_hi:[1,0]
	v_pk_mul_f32 v[46:47], v[40:41], s[18:19] op_sel_hi:[1,0]
	v_pk_mul_f32 v[32:33], v[40:41], v[32:33]
	v_pk_mul_f32 v[40:41], v[42:43], s[18:19] op_sel_hi:[1,0]
	v_pk_mul_f32 v[34:35], v[42:43], v[34:35]
	v_exp_f32_e32 v42, v50
	v_exp_f32_e32 v43, v51
	v_exp_f32_e32 v44, v44
	v_exp_f32_e32 v45, v45
	v_exp_f32_e32 v46, v46
	v_exp_f32_e32 v47, v47
	v_exp_f32_e32 v40, v40
	v_exp_f32_e32 v41, v41
	v_pk_add_f32 v[42:43], v[42:43], 1.0 op_sel_hi:[1,0]
	v_pk_add_f32 v[44:45], v[44:45], 1.0 op_sel_hi:[1,0]
	v_pk_add_f32 v[46:47], v[46:47], 1.0 op_sel_hi:[1,0]
	v_pk_add_f32 v[40:41], v[40:41], 1.0 op_sel_hi:[1,0]
	v_rcp_f32_e32 v42, v42
	v_rcp_f32_e32 v43, v43
	v_rcp_f32_e32 v44, v44
	v_rcp_f32_e32 v45, v45
	v_rcp_f32_e32 v46, v46
	v_rcp_f32_e32 v47, v47
	v_rcp_f32_e32 v40, v40
	v_rcp_f32_e32 v41, v41
	v_pk_mul_f32 v[36:37], v[36:37], v[42:43]
	v_pk_mul_f32 v[38:39], v[38:39], v[44:45]
	v_pk_mul_f32 v[42:43], v[32:33], v[46:47]
	v_pk_mul_f32 v[40:41], v[34:35], v[40:41]
	v_cvt_pk_bf16_f32 v32, v36, v37
	v_cvt_pk_bf16_f32 v33, v38, v39
	v_cvt_pk_bf16_f32 v34, v42, v43
	s_nop 0
	v_cvt_pk_bf16_f32 v35, v40, v41
	global_store_dwordx4 v[48:49], v[32:35], off
	global_load_dword v32, v[150:151], off offset:640
	s_waitcnt vmcnt(0) lgkmcnt(0)
	v_fmamk_f32 v32, v32, 0x3a000000, v158
	v_rsq_f32_e32 v34, v32
	s_nop 1
	v_add_u32_e32 v32, 0xa0, v144
	v_mad_i64_i32 v[32:33], s[4:5], v32, s42, v[148:149]
	v_lshl_add_u64 v[32:33], v[32:33], 0, v[146:147]
	s_nop 0
	s_nop 1
	s_nop 1
	s_nop 0
	v_pk_mul_f32 v[30:31], v[30:31], v[34:35] op_sel_hi:[1,0]
	v_pk_mul_f32 v[28:29], v[28:29], v[34:35] op_sel_hi:[1,0]
	v_pk_mul_f32 v[26:27], v[26:27], v[34:35] op_sel_hi:[1,0]
	v_pk_mul_f32 v[24:25], v[24:25], v[34:35] op_sel_hi:[1,0]
	v_pk_mul_f32 v[20:21], v[20:21], v[34:35] op_sel_hi:[1,0]
	v_pk_mul_f32 v[22:23], v[22:23], v[34:35] op_sel_hi:[1,0]
	v_pk_mul_f32 v[16:17], v[16:17], v[34:35] op_sel_hi:[1,0]
	v_pk_mul_f32 v[18:19], v[18:19], v[34:35] op_sel_hi:[1,0]
	v_pk_mul_f32 v[34:35], v[28:29], s[18:19] op_sel_hi:[1,0]
	v_pk_mul_f32 v[22:23], v[30:31], v[22:23]
	v_pk_mul_f32 v[20:21], v[28:29], v[20:21]
	v_pk_mul_f32 v[28:29], v[30:31], s[18:19] op_sel_hi:[1,0]
	v_pk_mul_f32 v[30:31], v[24:25], s[18:19] op_sel_hi:[1,0]
	v_pk_mul_f32 v[16:17], v[24:25], v[16:17]
	v_pk_mul_f32 v[24:25], v[26:27], s[18:19] op_sel_hi:[1,0]
	v_pk_mul_f32 v[18:19], v[26:27], v[18:19]
	v_exp_f32_e32 v26, v34
	v_exp_f32_e32 v27, v35
	v_exp_f32_e32 v28, v28
	v_exp_f32_e32 v29, v29
	v_exp_f32_e32 v30, v30
	v_exp_f32_e32 v31, v31
	v_exp_f32_e32 v24, v24
	v_exp_f32_e32 v25, v25
	v_pk_add_f32 v[26:27], v[26:27], 1.0 op_sel_hi:[1,0]
	v_pk_add_f32 v[28:29], v[28:29], 1.0 op_sel_hi:[1,0]
	v_pk_add_f32 v[30:31], v[30:31], 1.0 op_sel_hi:[1,0]
	v_pk_add_f32 v[24:25], v[24:25], 1.0 op_sel_hi:[1,0]
	v_rcp_f32_e32 v26, v26
	v_rcp_f32_e32 v27, v27
	v_rcp_f32_e32 v28, v28
	v_rcp_f32_e32 v29, v29
	v_rcp_f32_e32 v30, v30
	v_rcp_f32_e32 v31, v31
	v_rcp_f32_e32 v24, v24
	v_rcp_f32_e32 v25, v25
	v_pk_mul_f32 v[20:21], v[20:21], v[26:27]
	v_pk_mul_f32 v[22:23], v[22:23], v[28:29]
	v_pk_mul_f32 v[26:27], v[16:17], v[30:31]
	v_pk_mul_f32 v[24:25], v[18:19], v[24:25]
	v_cvt_pk_bf16_f32 v16, v20, v21
	v_cvt_pk_bf16_f32 v17, v22, v23
	v_cvt_pk_bf16_f32 v18, v26, v27
	s_nop 0
	v_cvt_pk_bf16_f32 v19, v24, v25
	global_store_dwordx4 v[32:33], v[16:19], off
	global_load_dword v16, v[150:151], off offset:704
	s_nop 0
	v_add_u32_e32 v17, 0xb0, v144
	s_waitcnt vmcnt(0) lgkmcnt(0)
	v_fmamk_f32 v16, v16, 0x3a000000, v158
	v_rsq_f32_e32 v18, v16
	s_nop 1
	v_mad_i64_i32 v[16:17], s[4:5], v17, s42, v[148:149]
	v_lshl_add_u64 v[16:17], v[16:17], 0, v[146:147]
	s_nop 1
	s_nop 1
	s_nop 1
	s_mov_b64 s[4:5], -1
	s_nop 0
	v_pk_mul_f32 v[14:15], v[14:15], v[18:19] op_sel_hi:[1,0]
	v_pk_mul_f32 v[12:13], v[12:13], v[18:19] op_sel_hi:[1,0]
	v_pk_mul_f32 v[10:11], v[10:11], v[18:19] op_sel_hi:[1,0]
	v_pk_mul_f32 v[8:9], v[8:9], v[18:19] op_sel_hi:[1,0]
	v_pk_mul_f32 v[4:5], v[4:5], v[18:19] op_sel_hi:[1,0]
	v_pk_mul_f32 v[6:7], v[6:7], v[18:19] op_sel_hi:[1,0]
	v_pk_mul_f32 v[0:1], v[0:1], v[18:19] op_sel_hi:[1,0]
	v_pk_mul_f32 v[2:3], v[2:3], v[18:19] op_sel_hi:[1,0]
	v_pk_mul_f32 v[18:19], v[12:13], s[18:19] op_sel_hi:[1,0]
	v_pk_mul_f32 v[6:7], v[14:15], v[6:7]
	v_pk_mul_f32 v[4:5], v[12:13], v[4:5]
	v_pk_mul_f32 v[12:13], v[14:15], s[18:19] op_sel_hi:[1,0]
	v_pk_mul_f32 v[14:15], v[8:9], s[18:19] op_sel_hi:[1,0]
	v_pk_mul_f32 v[0:1], v[8:9], v[0:1]
	v_pk_mul_f32 v[8:9], v[10:11], s[18:19] op_sel_hi:[1,0]
	v_pk_mul_f32 v[2:3], v[10:11], v[2:3]
	v_exp_f32_e32 v10, v18
	v_exp_f32_e32 v11, v19
	v_exp_f32_e32 v12, v12
	v_exp_f32_e32 v13, v13
	v_exp_f32_e32 v14, v14
	v_exp_f32_e32 v15, v15
	v_exp_f32_e32 v8, v8
	v_exp_f32_e32 v9, v9
	v_pk_add_f32 v[10:11], v[10:11], 1.0 op_sel_hi:[1,0]
	v_pk_add_f32 v[12:13], v[12:13], 1.0 op_sel_hi:[1,0]
	v_pk_add_f32 v[14:15], v[14:15], 1.0 op_sel_hi:[1,0]
	v_pk_add_f32 v[8:9], v[8:9], 1.0 op_sel_hi:[1,0]
	v_rcp_f32_e32 v10, v10
	v_rcp_f32_e32 v11, v11
	v_rcp_f32_e32 v12, v12
	v_rcp_f32_e32 v13, v13
	v_rcp_f32_e32 v14, v14
	v_rcp_f32_e32 v15, v15
	v_rcp_f32_e32 v8, v8
	v_rcp_f32_e32 v9, v9
	s_andn2_b64 vcc, exec, s[6:7]
	v_pk_mul_f32 v[4:5], v[4:5], v[10:11]
	v_pk_mul_f32 v[6:7], v[6:7], v[12:13]
	v_pk_mul_f32 v[10:11], v[0:1], v[14:15]
	v_pk_mul_f32 v[8:9], v[2:3], v[8:9]
	v_cvt_pk_bf16_f32 v0, v4, v5
	v_cvt_pk_bf16_f32 v1, v6, v7
	v_cvt_pk_bf16_f32 v2, v10, v11
	s_nop 0
	v_cvt_pk_bf16_f32 v3, v8, v9
	global_store_dwordx4 v[16:17], v[0:3], off
	s_cbranch_vccnz .LBB0_1406
	s_and_b64 vcc, exec, s[60:61]
	s_cbranch_vccnz .LBB0_1405
	s_barrier
	s_branch .LBB0_1405
